# weight f32->bf16 conversion loops (conv_wup in the scan phase, conv on idle WGs in GEMM tails, prologue): nt on their bf16 stores
# speedup vs baseline: 1.0176x; 1.0031x over previous
.LBB0_8:
	v_mul_u32_u24_e32 v2, 33, v73
	v_lshlrev_b32_e32 v2, 2, v2
	v_lshlrev_b32_e32 v3, 2, v74
	s_waitcnt vmcnt(14)
	v_cvt_pk_bf16_f32 v0, v28, v40
	v_add3_u32 v2, s9, v2, v3
	s_waitcnt vmcnt(12)
	v_cvt_pk_bf16_f32 v20, v20, v24
	ds_write2_b32 v2, v0, v20 offset1:4
	v_cvt_pk_bf16_f32 v0, v21, v25
	v_cvt_pk_bf16_f32 v3, v29, v41
	ds_write2_b32 v2, v3, v0 offset0:33 offset1:37
	v_cvt_pk_bf16_f32 v0, v22, v26
	v_cvt_pk_bf16_f32 v28, v30, v42
	ds_write2_b32 v2, v28, v0 offset0:66 offset1:70
	v_cvt_pk_bf16_f32 v0, v23, v27
	v_cvt_pk_bf16_f32 v29, v31, v43
	ds_write2_b32 v2, v29, v0 offset0:99 offset1:103
	s_waitcnt vmcnt(10)
	v_cvt_pk_bf16_f32 v0, v12, v16
	v_cvt_pk_bf16_f32 v12, v14, v18
	s_waitcnt vmcnt(8)
	v_cvt_pk_bf16_f32 v14, v64, v60
	ds_write2_b32 v2, v0, v14 offset0:8 offset1:12
	v_cvt_pk_bf16_f32 v0, v65, v61
	v_cvt_pk_bf16_f32 v3, v13, v17
	ds_write2_b32 v2, v3, v0 offset0:41 offset1:45
	v_cvt_pk_bf16_f32 v0, v66, v62
	ds_write2_b32 v2, v12, v0 offset0:74 offset1:78
	v_cvt_pk_bf16_f32 v0, v67, v63
	v_cvt_pk_bf16_f32 v13, v15, v19
	ds_write2_b32 v2, v13, v0 offset0:107 offset1:111
	s_waitcnt vmcnt(6)
	v_cvt_pk_bf16_f32 v0, v56, v52
	s_waitcnt vmcnt(4)
	v_cvt_pk_bf16_f32 v14, v48, v44
	ds_write2_b32 v2, v0, v14 offset0:16 offset1:20
	v_cvt_pk_bf16_f32 v0, v49, v45
	v_cvt_pk_bf16_f32 v3, v57, v53
	ds_write2_b32 v2, v3, v0 offset0:49 offset1:53
	v_cvt_pk_bf16_f32 v0, v50, v46
	v_cvt_pk_bf16_f32 v12, v58, v54
	ds_write2_b32 v2, v12, v0 offset0:82 offset1:86
	v_cvt_pk_bf16_f32 v0, v51, v47
	v_cvt_pk_bf16_f32 v13, v59, v55
	ds_write2_b32 v2, v13, v0 offset0:115 offset1:119
	s_waitcnt vmcnt(2)
	v_cvt_pk_bf16_f32 v0, v36, v32
	s_waitcnt vmcnt(0)
	v_cvt_pk_bf16_f32 v4, v8, v4
	ds_write2_b32 v2, v0, v4 offset0:24 offset1:28
	v_cvt_pk_bf16_f32 v0, v9, v5
	v_cvt_pk_bf16_f32 v3, v37, v33
	ds_write2_b32 v2, v3, v0 offset0:57 offset1:61
	v_cvt_pk_bf16_f32 v0, v10, v6
	s_ashr_i32 s15, s14, 31
	v_cvt_pk_bf16_f32 v12, v38, v34
	ds_write2_b32 v2, v12, v0 offset0:90 offset1:94
	v_cvt_pk_bf16_f32 v0, v11, v7
	s_lshl_b64 s[14:15], s[14:15], 1
	v_cvt_pk_bf16_f32 v13, v39, v35
	ds_write2_b32 v2, v13, v0 offset0:123 offset1:127
	v_ashrrev_i32_e32 v6, 3, v72
	v_lshlrev_b32_e32 v0, 4, v72
	s_add_u32 s14, s3, s14
	v_and_b32_e32 v0, 0x70, v0
	s_addc_u32 s15, s5, s15
	v_mul_lo_u32 v2, v6, s22
	v_lshl_add_u64 v[10:11], s[14:15], 0, v[0:1]
	v_add3_u32 v0, s9, v0, v2
	v_subrev_u32_e32 v6, s24, v6
	s_waitcnt lgkmcnt(0)
	ds_read2_b32 v[2:3], v0 offset1:1
	ds_read2_b32 v[4:5], v0 offset0:2 offset1:3
	v_add_u32_e32 v12, s11, v6
	v_ashrrev_i32_e32 v13, 31, v12
	v_lshlrev_b64 v[6:7], 13, v[12:13]
	v_lshl_add_u64 v[14:15], v[10:11], 0, v[6:7]
	v_add_u32_e32 v6, 0x420, v0
	v_add_u32_e32 v8, 0x428, v0
	ds_read2_b32 v[6:7], v6 offset1:1
	ds_read2_b32 v[8:9], v8 offset1:1
	s_waitcnt lgkmcnt(2)
	global_store_dwordx4 v[14:15], v[2:5], off nt
	s_add_i32 s23, s23, s10
	s_add_i32 s11, s11, s4
	v_add_u32_e32 v2, 8, v12
	v_ashrrev_i32_e32 v3, 31, v2
	v_lshlrev_b64 v[2:3], 13, v[2:3]
	v_lshl_add_u64 v[2:3], v[10:11], 0, v[2:3]
	s_waitcnt lgkmcnt(0)
	global_store_dwordx4 v[2:3], v[6:9], off nt
	v_add_u32_e32 v2, 0x840, v0
	v_add_u32_e32 v4, 0x848, v0
	ds_read2_b32 v[2:3], v2 offset1:1
	ds_read2_b32 v[4:5], v4 offset1:1
	v_add_u32_e32 v6, 16, v12
	v_ashrrev_i32_e32 v7, 31, v6
	v_lshlrev_b64 v[6:7], 13, v[6:7]
	v_lshl_add_u64 v[14:15], v[10:11], 0, v[6:7]
	v_add_u32_e32 v6, 0xc60, v0
	v_add_u32_e32 v8, 0xc68, v0
	ds_read2_b32 v[6:7], v6 offset1:1
	ds_read2_b32 v[8:9], v8 offset1:1
	s_waitcnt lgkmcnt(2)
	global_store_dwordx4 v[14:15], v[2:5], off nt
	s_cmpk_lt_i32 s23, 0x3d00
	s_nop 0
	v_add_u32_e32 v2, 24, v12
	v_ashrrev_i32_e32 v3, 31, v2
	v_lshlrev_b64 v[2:3], 13, v[2:3]
	v_lshl_add_u64 v[2:3], v[10:11], 0, v[2:3]
	s_waitcnt lgkmcnt(0)
	global_store_dwordx4 v[2:3], v[6:9], off nt
	v_add_u32_e32 v2, 0x1080, v0
	v_add_u32_e32 v4, 0x1088, v0
	ds_read2_b32 v[2:3], v2 offset1:1
	ds_read2_b32 v[4:5], v4 offset1:1
	v_add_u32_e32 v6, 32, v12
	v_ashrrev_i32_e32 v7, 31, v6
	v_lshlrev_b64 v[6:7], 13, v[6:7]
	v_lshl_add_u64 v[14:15], v[10:11], 0, v[6:7]
	v_add_u32_e32 v6, 0x14a0, v0
	v_add_u32_e32 v8, 0x14a8, v0
	ds_read2_b32 v[6:7], v6 offset1:1
	ds_read2_b32 v[8:9], v8 offset1:1
	s_waitcnt lgkmcnt(2)
	global_store_dwordx4 v[14:15], v[2:5], off nt
	s_nop 1
	v_add_u32_e32 v2, 40, v12
	v_ashrrev_i32_e32 v3, 31, v2
	v_lshlrev_b64 v[2:3], 13, v[2:3]
	v_lshl_add_u64 v[2:3], v[10:11], 0, v[2:3]
	s_waitcnt lgkmcnt(0)
	global_store_dwordx4 v[2:3], v[6:9], off nt
	v_add_u32_e32 v2, 0x18c0, v0
	v_add_u32_e32 v4, 0x18c8, v0
	ds_read2_b32 v[2:3], v2 offset1:1
	ds_read2_b32 v[4:5], v4 offset1:1
	v_add_u32_e32 v6, 48, v12
	v_ashrrev_i32_e32 v7, 31, v6
	v_lshlrev_b64 v[6:7], 13, v[6:7]
	v_lshl_add_u64 v[14:15], v[10:11], 0, v[6:7]
	v_add_u32_e32 v6, 0x1ce0, v0
	v_add_u32_e32 v0, 0x1ce8, v0
	ds_read2_b32 v[6:7], v6 offset1:1
	ds_read2_b32 v[8:9], v0 offset1:1
	s_waitcnt lgkmcnt(2)
	global_store_dwordx4 v[14:15], v[2:5], off nt
	s_nop 1
	v_add_u32_e32 v2, 56, v12
	v_ashrrev_i32_e32 v3, 31, v2
	v_lshlrev_b64 v[2:3], 13, v[2:3]
	v_lshl_add_u64 v[2:3], v[10:11], 0, v[2:3]
	s_waitcnt lgkmcnt(0)
	global_store_dwordx4 v[2:3], v[6:9], off nt
	s_waitcnt lgkmcnt(0)
	s_cbranch_scc0 .LBB0_27

.LBB0_131:
	s_waitcnt vmcnt(0)
	v_cvt_pk_bf16_f32 v56, v60, v56
	v_mul_u32_u24_e32 v60, 33, v68
	v_lshlrev_b32_e32 v60, 2, v60
	v_lshlrev_b32_e32 v64, 2, v67
	v_add3_u32 v60, s9, v60, v64
	v_cvt_pk_bf16_f32 v8, v16, v8
	v_cvt_pk_bf16_f32 v24, v28, v24
	ds_write2_b32 v60, v24, v8 offset0:16 offset1:20
	v_cvt_pk_bf16_f32 v8, v17, v9
	v_cvt_pk_bf16_f32 v25, v29, v25
	ds_write2_b32 v60, v25, v8 offset0:49 offset1:53
	v_cvt_pk_bf16_f32 v8, v18, v10
	v_cvt_pk_bf16_f32 v26, v30, v26
	ds_write2_b32 v60, v26, v8 offset0:82 offset1:86
	v_cvt_pk_bf16_f32 v8, v19, v11
	v_cvt_pk_bf16_f32 v0, v4, v0
	v_cvt_pk_bf16_f32 v27, v31, v27
	ds_write2_b32 v60, v27, v8 offset0:115 offset1:119
	v_cvt_pk_bf16_f32 v8, v20, v12
	ds_write2_b32 v60, v8, v0 offset0:24 offset1:28
	v_cvt_pk_bf16_f32 v0, v5, v1
	v_cvt_pk_bf16_f32 v9, v21, v13
	ds_write2_b32 v60, v9, v0 offset0:57 offset1:61
	v_cvt_pk_bf16_f32 v0, v6, v2
	v_cvt_pk_bf16_f32 v48, v52, v48
	v_cvt_pk_bf16_f32 v32, v36, v32
	v_cvt_pk_bf16_f32 v10, v22, v14
	ds_write2_b32 v60, v10, v0 offset0:90 offset1:94
	v_cvt_pk_bf16_f32 v0, v7, v3
	ds_write2_b32 v60, v56, v48 offset1:4
	v_cvt_pk_bf16_f32 v48, v53, v49
	v_cvt_pk_bf16_f32 v40, v44, v40
	ds_write2_b32 v60, v40, v32 offset0:8 offset1:12
	v_cvt_pk_bf16_f32 v32, v37, v33
	v_cvt_pk_bf16_f32 v11, v23, v15
	ds_write2_b32 v60, v11, v0 offset0:123 offset1:127
	v_ashrrev_i32_e32 v4, 3, v66
	v_lshlrev_b32_e32 v0, 4, v66
	v_cvt_pk_bf16_f32 v57, v61, v57
	ds_write2_b32 v60, v57, v48 offset0:33 offset1:37
	v_cvt_pk_bf16_f32 v48, v54, v50
	v_cvt_pk_bf16_f32 v41, v45, v41
	ds_write2_b32 v60, v41, v32 offset0:41 offset1:45
	v_cvt_pk_bf16_f32 v32, v38, v34
	v_and_b32_e32 v64, 0x70, v0
	s_ashr_i32 s1, s0, 31
	v_mul_lo_u32 v0, v4, s24
	v_subrev_u32_e32 v4, s27, v4
	v_cvt_pk_bf16_f32 v58, v62, v58
	v_cvt_pk_bf16_f32 v59, v63, v59
	ds_write2_b32 v60, v58, v48 offset0:66 offset1:70
	v_cvt_pk_bf16_f32 v48, v55, v51
	ds_write2_b32 v60, v59, v48 offset0:99 offset1:103
	v_cvt_pk_bf16_f32 v42, v46, v42
	v_cvt_pk_bf16_f32 v43, v47, v43
	ds_write2_b32 v60, v42, v32 offset0:74 offset1:78
	v_cvt_pk_bf16_f32 v32, v39, v35
	ds_write2_b32 v60, v43, v32 offset0:107 offset1:111
	s_lshl_b64 s[0:1], s[0:1], 1
	v_add3_u32 v11, s9, v64, v0
	v_add_u32_e32 v10, s25, v4
	s_waitcnt lgkmcnt(0)
	s_add_u32 s0, s6, s0
	ds_read2_b32 v[0:1], v11 offset1:1
	ds_read2_b32 v[2:3], v11 offset0:2 offset1:3
	v_subrev_u32_e32 v4, 56, v10
	s_addc_u32 s1, s7, s1
	v_ashrrev_i32_e32 v5, 31, v4
	v_lshl_add_u64 v[8:9], s[0:1], 0, v[64:65]
	v_lshlrev_b64 v[4:5], 13, v[4:5]
	v_lshl_add_u64 v[12:13], v[8:9], 0, v[4:5]
	v_add_u32_e32 v4, 0x420, v11
	v_add_u32_e32 v6, 0x428, v11
	ds_read2_b32 v[4:5], v4 offset1:1
	ds_read2_b32 v[6:7], v6 offset1:1
	s_waitcnt lgkmcnt(2)
	global_store_dwordx4 v[12:13], v[0:3], off nt
	s_add_i32 s26, s26, s8
	s_add_i32 s25, s25, s11
	v_subrev_u32_e32 v0, 48, v10
	v_ashrrev_i32_e32 v1, 31, v0
	v_lshlrev_b64 v[0:1], 13, v[0:1]
	v_lshl_add_u64 v[0:1], v[8:9], 0, v[0:1]
	s_waitcnt lgkmcnt(0)
	global_store_dwordx4 v[0:1], v[4:7], off nt
	v_add_u32_e32 v0, 0x840, v11
	v_add_u32_e32 v2, 0x848, v11
	ds_read2_b32 v[0:1], v0 offset1:1
	ds_read2_b32 v[2:3], v2 offset1:1
	v_subrev_u32_e32 v4, 40, v10
	v_ashrrev_i32_e32 v5, 31, v4
	v_lshlrev_b64 v[4:5], 13, v[4:5]
	v_lshl_add_u64 v[12:13], v[8:9], 0, v[4:5]
	v_add_u32_e32 v4, 0xc60, v11
	v_add_u32_e32 v6, 0xc68, v11
	ds_read2_b32 v[4:5], v4 offset1:1
	ds_read2_b32 v[6:7], v6 offset1:1
	s_waitcnt lgkmcnt(2)
	global_store_dwordx4 v[12:13], v[0:3], off nt
	s_cmpk_lt_i32 s26, 0x1000
	s_nop 0
	v_subrev_u32_e32 v0, 32, v10
	v_ashrrev_i32_e32 v1, 31, v0
	v_lshlrev_b64 v[0:1], 13, v[0:1]
	v_lshl_add_u64 v[0:1], v[8:9], 0, v[0:1]
	s_waitcnt lgkmcnt(0)
	global_store_dwordx4 v[0:1], v[4:7], off nt
	v_add_u32_e32 v0, 0x1080, v11
	v_add_u32_e32 v2, 0x1088, v11
	ds_read2_b32 v[0:1], v0 offset1:1
	ds_read2_b32 v[2:3], v2 offset1:1
	v_subrev_u32_e32 v4, 24, v10
	v_ashrrev_i32_e32 v5, 31, v4
	v_lshlrev_b64 v[4:5], 13, v[4:5]
	v_lshl_add_u64 v[12:13], v[8:9], 0, v[4:5]
	v_add_u32_e32 v4, 0x14a0, v11
	v_add_u32_e32 v6, 0x14a8, v11
	ds_read2_b32 v[4:5], v4 offset1:1
	ds_read2_b32 v[6:7], v6 offset1:1
	s_waitcnt lgkmcnt(2)
	global_store_dwordx4 v[12:13], v[0:3], off nt
	s_nop 1
	v_add_u32_e32 v0, -16, v10
	v_ashrrev_i32_e32 v1, 31, v0
	v_lshlrev_b64 v[0:1], 13, v[0:1]
	v_lshl_add_u64 v[0:1], v[8:9], 0, v[0:1]
	s_waitcnt lgkmcnt(0)
	global_store_dwordx4 v[0:1], v[4:7], off nt
	v_add_u32_e32 v0, 0x18c0, v11
	v_add_u32_e32 v2, 0x18c8, v11
	v_add_u32_e32 v4, -8, v10
	v_ashrrev_i32_e32 v5, 31, v4
	ds_read2_b32 v[0:1], v0 offset1:1
	ds_read2_b32 v[2:3], v2 offset1:1
	v_lshlrev_b64 v[4:5], 13, v[4:5]
	v_lshl_add_u64 v[12:13], v[8:9], 0, v[4:5]
	v_add_u32_e32 v4, 0x1ce0, v11
	v_add_u32_e32 v6, 0x1ce8, v11
	ds_read2_b32 v[4:5], v4 offset1:1
	ds_read2_b32 v[6:7], v6 offset1:1
	v_ashrrev_i32_e32 v11, 31, v10
	s_waitcnt lgkmcnt(2)
	global_store_dwordx4 v[12:13], v[0:3], off nt
	s_nop 1
	v_lshlrev_b64 v[0:1], 13, v[10:11]
	v_lshl_add_u64 v[0:1], v[8:9], 0, v[0:1]
	s_waitcnt lgkmcnt(0)
	global_store_dwordx4 v[0:1], v[4:7], off nt
	s_waitcnt lgkmcnt(0)
	s_cbranch_scc0 .LBB0_134

.LBB0_135:
	v_mul_u32_u24_e32 v2, 33, v72
	v_lshlrev_b32_e32 v2, 2, v2
	v_lshlrev_b32_e32 v3, 2, v71
	s_waitcnt vmcnt(14)
	v_cvt_pk_bf16_f32 v0, v60, v64
	v_add3_u32 v2, s9, v2, v3
	s_waitcnt vmcnt(12)
	v_cvt_pk_bf16_f32 v52, v52, v56
	ds_write2_b32 v2, v0, v52 offset1:4
	v_cvt_pk_bf16_f32 v0, v53, v57
	v_cvt_pk_bf16_f32 v3, v61, v65
	ds_write2_b32 v2, v3, v0 offset0:33 offset1:37
	v_cvt_pk_bf16_f32 v0, v54, v58
	v_cvt_pk_bf16_f32 v60, v62, v66
	ds_write2_b32 v2, v60, v0 offset0:66 offset1:70
	v_cvt_pk_bf16_f32 v0, v55, v59
	v_cvt_pk_bf16_f32 v61, v63, v67
	ds_write2_b32 v2, v61, v0 offset0:99 offset1:103
	s_waitcnt vmcnt(10)
	v_cvt_pk_bf16_f32 v0, v44, v48
	s_waitcnt vmcnt(8)
	v_cvt_pk_bf16_f32 v36, v36, v40
	ds_write2_b32 v2, v0, v36 offset0:8 offset1:12
	v_cvt_pk_bf16_f32 v0, v37, v41
	v_cvt_pk_bf16_f32 v3, v45, v49
	ds_write2_b32 v2, v3, v0 offset0:41 offset1:45
	v_cvt_pk_bf16_f32 v0, v38, v42
	v_cvt_pk_bf16_f32 v44, v46, v50
	ds_write2_b32 v2, v44, v0 offset0:74 offset1:78
	v_cvt_pk_bf16_f32 v0, v39, v43
	v_cvt_pk_bf16_f32 v45, v47, v51
	ds_write2_b32 v2, v45, v0 offset0:107 offset1:111
	s_waitcnt vmcnt(6)
	v_cvt_pk_bf16_f32 v0, v28, v32
	s_waitcnt vmcnt(4)
	v_cvt_pk_bf16_f32 v20, v20, v24
	ds_write2_b32 v2, v0, v20 offset0:16 offset1:20
	v_cvt_pk_bf16_f32 v0, v21, v25
	v_cvt_pk_bf16_f32 v3, v29, v33
	ds_write2_b32 v2, v3, v0 offset0:49 offset1:53
	v_cvt_pk_bf16_f32 v0, v22, v26
	v_cvt_pk_bf16_f32 v28, v30, v34
	ds_write2_b32 v2, v28, v0 offset0:82 offset1:86
	v_cvt_pk_bf16_f32 v0, v23, v27
	v_cvt_pk_bf16_f32 v29, v31, v35
	ds_write2_b32 v2, v29, v0 offset0:115 offset1:119
	s_waitcnt vmcnt(2)
	v_cvt_pk_bf16_f32 v0, v12, v16
	s_waitcnt vmcnt(0)
	v_cvt_pk_bf16_f32 v4, v4, v8
	ds_write2_b32 v2, v0, v4 offset0:24 offset1:28
	v_cvt_pk_bf16_f32 v0, v5, v9
	v_cvt_pk_bf16_f32 v3, v13, v17
	ds_write2_b32 v2, v3, v0 offset0:57 offset1:61
	v_cvt_pk_bf16_f32 v0, v6, v10
	s_ashr_i32 s7, s6, 31
	v_cvt_pk_bf16_f32 v12, v14, v18
	ds_write2_b32 v2, v12, v0 offset0:90 offset1:94
	v_cvt_pk_bf16_f32 v0, v7, v11
	s_lshl_b64 s[6:7], s[6:7], 1
	v_cvt_pk_bf16_f32 v13, v15, v19
	ds_write2_b32 v2, v13, v0 offset0:123 offset1:127
	v_ashrrev_i32_e32 v6, 3, v70
	v_lshlrev_b32_e32 v0, 4, v70
	s_add_u32 s6, s12, s6
	v_and_b32_e32 v0, 0x70, v0
	s_addc_u32 s7, s13, s7
	v_mul_lo_u32 v2, v6, s26
	v_subrev_u32_e32 v6, s27, v6
	v_lshl_add_u64 v[10:11], s[6:7], 0, v[0:1]
	v_add3_u32 v0, s9, v0, v2
	v_add_u32_e32 v12, s10, v6
	s_waitcnt lgkmcnt(0)
	ds_read2_b32 v[2:3], v0 offset1:1
	ds_read2_b32 v[4:5], v0 offset0:2 offset1:3
	v_subrev_u32_e32 v6, 56, v12
	v_ashrrev_i32_e32 v7, 31, v6
	v_lshlrev_b64 v[6:7], 13, v[6:7]
	v_lshl_add_u64 v[14:15], v[10:11], 0, v[6:7]
	v_add_u32_e32 v6, 0x420, v0
	v_add_u32_e32 v8, 0x428, v0
	ds_read2_b32 v[6:7], v6 offset1:1
	ds_read2_b32 v[8:9], v8 offset1:1
	s_waitcnt lgkmcnt(2)
	global_store_dwordx4 v[14:15], v[2:5], off nt
	v_ashrrev_i32_e32 v13, 31, v12
	s_add_i32 s3, s3, s8
	v_subrev_u32_e32 v2, 48, v12
	v_ashrrev_i32_e32 v3, 31, v2
	v_lshlrev_b64 v[2:3], 13, v[2:3]
	v_lshl_add_u64 v[2:3], v[10:11], 0, v[2:3]
	s_waitcnt lgkmcnt(0)
	global_store_dwordx4 v[2:3], v[6:9], off nt
	v_add_u32_e32 v2, 0x840, v0
	v_add_u32_e32 v4, 0x848, v0
	ds_read2_b32 v[2:3], v2 offset1:1
	ds_read2_b32 v[4:5], v4 offset1:1
	v_subrev_u32_e32 v6, 40, v12
	v_ashrrev_i32_e32 v7, 31, v6
	v_lshlrev_b64 v[6:7], 13, v[6:7]
	v_lshl_add_u64 v[14:15], v[10:11], 0, v[6:7]
	v_add_u32_e32 v6, 0xc60, v0
	v_add_u32_e32 v8, 0xc68, v0
	ds_read2_b32 v[6:7], v6 offset1:1
	ds_read2_b32 v[8:9], v8 offset1:1
	s_waitcnt lgkmcnt(2)
	global_store_dwordx4 v[14:15], v[2:5], off nt
	s_add_i32 s10, s10, s11
	s_cmpk_lt_i32 s3, 0x1000
	v_subrev_u32_e32 v2, 32, v12
	v_ashrrev_i32_e32 v3, 31, v2
	v_lshlrev_b64 v[2:3], 13, v[2:3]
	v_lshl_add_u64 v[2:3], v[10:11], 0, v[2:3]
	s_waitcnt lgkmcnt(0)
	global_store_dwordx4 v[2:3], v[6:9], off nt
	v_add_u32_e32 v2, 0x1080, v0
	v_add_u32_e32 v4, 0x1088, v0
	ds_read2_b32 v[2:3], v2 offset1:1
	ds_read2_b32 v[4:5], v4 offset1:1
	v_subrev_u32_e32 v6, 24, v12
	v_ashrrev_i32_e32 v7, 31, v6
	v_lshlrev_b64 v[6:7], 13, v[6:7]
	v_lshl_add_u64 v[14:15], v[10:11], 0, v[6:7]
	v_add_u32_e32 v6, 0x14a0, v0
	v_add_u32_e32 v8, 0x14a8, v0
	ds_read2_b32 v[6:7], v6 offset1:1
	ds_read2_b32 v[8:9], v8 offset1:1
	s_waitcnt lgkmcnt(2)
	global_store_dwordx4 v[14:15], v[2:5], off nt
	s_nop 1
	v_add_u32_e32 v2, -16, v12
	v_ashrrev_i32_e32 v3, 31, v2
	v_lshlrev_b64 v[2:3], 13, v[2:3]
	v_lshl_add_u64 v[2:3], v[10:11], 0, v[2:3]
	s_waitcnt lgkmcnt(0)
	global_store_dwordx4 v[2:3], v[6:9], off nt
	v_add_u32_e32 v2, 0x18c0, v0
	v_add_u32_e32 v4, 0x18c8, v0
	v_add_u32_e32 v6, -8, v12
	v_ashrrev_i32_e32 v7, 31, v6
	ds_read2_b32 v[2:3], v2 offset1:1
	ds_read2_b32 v[4:5], v4 offset1:1
	v_lshlrev_b64 v[6:7], 13, v[6:7]
	v_lshl_add_u64 v[14:15], v[10:11], 0, v[6:7]
	v_add_u32_e32 v6, 0x1ce0, v0
	v_add_u32_e32 v0, 0x1ce8, v0
	ds_read2_b32 v[6:7], v6 offset1:1
	ds_read2_b32 v[8:9], v0 offset1:1
	s_waitcnt lgkmcnt(2)
	global_store_dwordx4 v[14:15], v[2:5], off nt
	s_nop 1
	v_lshlrev_b64 v[2:3], 13, v[12:13]
	v_lshl_add_u64 v[2:3], v[10:11], 0, v[2:3]
	s_waitcnt lgkmcnt(0)
	global_store_dwordx4 v[2:3], v[6:9], off nt
	s_waitcnt lgkmcnt(0)
	s_cbranch_scc0 .LBB0_140

.LBB0_852:
	v_mul_u32_u24_e32 v2, 33, v73
	v_lshlrev_b32_e32 v2, 2, v2
	v_lshlrev_b32_e32 v3, 2, v74
	s_waitcnt vmcnt(0)
	v_cvt_pk_bf16_f32 v0, v60, v64
	v_add3_u32 v2, s15, v2, v3
	v_cvt_pk_bf16_f32 v52, v52, v56
	ds_write2_b32 v2, v0, v52 offset1:4
	v_cvt_pk_bf16_f32 v0, v53, v57
	v_cvt_pk_bf16_f32 v3, v61, v65
	ds_write2_b32 v2, v3, v0 offset0:33 offset1:37
	v_cvt_pk_bf16_f32 v0, v54, v58
	v_cvt_pk_bf16_f32 v60, v62, v66
	ds_write2_b32 v2, v60, v0 offset0:66 offset1:70
	v_cvt_pk_bf16_f32 v0, v55, v59
	v_cvt_pk_bf16_f32 v61, v63, v67
	ds_write2_b32 v2, v61, v0 offset0:99 offset1:103
	v_cvt_pk_bf16_f32 v0, v44, v48
	v_cvt_pk_bf16_f32 v36, v36, v40
	ds_write2_b32 v2, v0, v36 offset0:8 offset1:12
	v_cvt_pk_bf16_f32 v0, v37, v41
	v_cvt_pk_bf16_f32 v3, v45, v49
	ds_write2_b32 v2, v3, v0 offset0:41 offset1:45
	v_cvt_pk_bf16_f32 v0, v38, v42
	v_cvt_pk_bf16_f32 v44, v46, v50
	ds_write2_b32 v2, v44, v0 offset0:74 offset1:78
	v_cvt_pk_bf16_f32 v0, v39, v43
	v_cvt_pk_bf16_f32 v45, v47, v51
	ds_write2_b32 v2, v45, v0 offset0:107 offset1:111
	v_cvt_pk_bf16_f32 v0, v28, v32
	v_cvt_pk_bf16_f32 v16, v16, v24
	ds_write2_b32 v2, v0, v16 offset0:16 offset1:20
	v_cvt_pk_bf16_f32 v0, v17, v25
	v_cvt_pk_bf16_f32 v3, v29, v33
	ds_write2_b32 v2, v3, v0 offset0:49 offset1:53
	v_cvt_pk_bf16_f32 v0, v18, v26
	v_cvt_pk_bf16_f32 v28, v30, v34
	ds_write2_b32 v2, v28, v0 offset0:82 offset1:86
	v_cvt_pk_bf16_f32 v0, v19, v27
	s_mul_hi_i32 s9, s10, 0x7a00000
	s_mul_i32 s10, s10, 0x7a00000
	v_cvt_pk_bf16_f32 v29, v31, v35
	ds_write2_b32 v2, v29, v0 offset0:115 offset1:119
	v_cvt_pk_bf16_f32 v0, v12, v20
	s_add_u32 s10, s18, s10
	v_cvt_pk_bf16_f32 v4, v4, v8
	ds_write2_b32 v2, v0, v4 offset0:24 offset1:28
	v_cvt_pk_bf16_f32 v0, v5, v9
	s_addc_u32 s11, s19, s9
	v_cvt_pk_bf16_f32 v3, v13, v21
	ds_write2_b32 v2, v3, v0 offset0:57 offset1:61
	v_cvt_pk_bf16_f32 v0, v6, v10
	s_ashr_i32 s9, s8, 31
	v_cvt_pk_bf16_f32 v12, v14, v22
	ds_write2_b32 v2, v12, v0 offset0:90 offset1:94
	v_cvt_pk_bf16_f32 v0, v7, v11
	s_lshl_b64 s[8:9], s[8:9], 1
	v_cvt_pk_bf16_f32 v13, v15, v23
	ds_write2_b32 v2, v13, v0 offset0:123 offset1:127
	v_ashrrev_i32_e32 v6, 3, v72
	v_lshlrev_b32_e32 v0, 4, v72
	s_add_u32 s8, s10, s8
	v_and_b32_e32 v0, 0x70, v0
	s_addc_u32 s9, s11, s9
	v_mul_lo_u32 v2, v6, s23
	v_lshl_add_u64 v[10:11], s[8:9], 0, v[0:1]
	v_add3_u32 v0, s15, v0, v2
	s_waitcnt lgkmcnt(0)
	ds_read2_b32 v[2:3], v0 offset1:1
	ds_read2_b32 v[4:5], v0 offset0:2 offset1:3
	v_add_u32_e32 v12, s0, v6
	v_ashrrev_i32_e32 v13, 31, v12
	v_lshlrev_b64 v[6:7], 13, v[12:13]
	v_lshl_add_u64 v[14:15], v[10:11], 0, v[6:7]
	v_add_u32_e32 v6, 0x420, v0
	v_add_u32_e32 v8, 0x428, v0
	ds_read2_b32 v[6:7], v6 offset1:1
	ds_read2_b32 v[8:9], v8 offset1:1
	s_waitcnt lgkmcnt(2)
	global_store_dwordx4 v[14:15], v[2:5], off nt
	s_nop 1
	v_add_u32_e32 v2, 8, v12
	v_ashrrev_i32_e32 v3, 31, v2
	v_lshlrev_b64 v[2:3], 13, v[2:3]
	v_lshl_add_u64 v[2:3], v[10:11], 0, v[2:3]
	s_waitcnt lgkmcnt(0)
	global_store_dwordx4 v[2:3], v[6:9], off nt
	v_add_u32_e32 v2, 0x840, v0
	v_add_u32_e32 v4, 0x848, v0
	ds_read2_b32 v[2:3], v2 offset1:1
	ds_read2_b32 v[4:5], v4 offset1:1
	v_add_u32_e32 v6, 16, v12
	v_ashrrev_i32_e32 v7, 31, v6
	v_lshlrev_b64 v[6:7], 13, v[6:7]
	v_lshl_add_u64 v[14:15], v[10:11], 0, v[6:7]
	v_add_u32_e32 v6, 0xc60, v0
	v_add_u32_e32 v8, 0xc68, v0
	ds_read2_b32 v[6:7], v6 offset1:1
	ds_read2_b32 v[8:9], v8 offset1:1
	s_waitcnt lgkmcnt(2)
	global_store_dwordx4 v[14:15], v[2:5], off nt
	s_nop 1
	v_add_u32_e32 v2, 24, v12
	v_ashrrev_i32_e32 v3, 31, v2
	v_lshlrev_b64 v[2:3], 13, v[2:3]
	v_lshl_add_u64 v[2:3], v[10:11], 0, v[2:3]
	s_waitcnt lgkmcnt(0)
	global_store_dwordx4 v[2:3], v[6:9], off nt
	v_add_u32_e32 v2, 0x1080, v0
	v_add_u32_e32 v4, 0x1088, v0
	ds_read2_b32 v[2:3], v2 offset1:1
	ds_read2_b32 v[4:5], v4 offset1:1
	v_add_u32_e32 v6, 32, v12
	v_ashrrev_i32_e32 v7, 31, v6
	v_lshlrev_b64 v[6:7], 13, v[6:7]
	v_lshl_add_u64 v[14:15], v[10:11], 0, v[6:7]
	v_add_u32_e32 v6, 0x14a0, v0
	v_add_u32_e32 v8, 0x14a8, v0
	ds_read2_b32 v[6:7], v6 offset1:1
	ds_read2_b32 v[8:9], v8 offset1:1
	s_waitcnt lgkmcnt(2)
	global_store_dwordx4 v[14:15], v[2:5], off nt
	s_nop 1
	v_add_u32_e32 v2, 40, v12
	v_ashrrev_i32_e32 v3, 31, v2
	v_lshlrev_b64 v[2:3], 13, v[2:3]
	v_lshl_add_u64 v[2:3], v[10:11], 0, v[2:3]
	s_waitcnt lgkmcnt(0)
	global_store_dwordx4 v[2:3], v[6:9], off nt
	v_add_u32_e32 v2, 0x18c0, v0
	v_add_u32_e32 v4, 0x18c8, v0
	ds_read2_b32 v[2:3], v2 offset1:1
	ds_read2_b32 v[4:5], v4 offset1:1
	v_add_u32_e32 v6, 48, v12
	v_ashrrev_i32_e32 v7, 31, v6
	v_lshlrev_b64 v[6:7], 13, v[6:7]
	v_lshl_add_u64 v[14:15], v[10:11], 0, v[6:7]
	v_add_u32_e32 v6, 0x1ce0, v0
	v_add_u32_e32 v0, 0x1ce8, v0
	ds_read2_b32 v[6:7], v6 offset1:1
	ds_read2_b32 v[8:9], v0 offset1:1
	s_waitcnt lgkmcnt(2)
	global_store_dwordx4 v[14:15], v[2:5], off nt
	s_nop 1
	v_add_u32_e32 v2, 56, v12
	v_ashrrev_i32_e32 v3, 31, v2
	v_lshlrev_b64 v[2:3], 13, v[2:3]
	v_lshl_add_u64 v[2:3], v[10:11], 0, v[2:3]
	s_waitcnt lgkmcnt(0)
	global_store_dwordx4 v[2:3], v[6:9], off nt
	s_waitcnt lgkmcnt(0)

.LBB0_1057:
	v_mul_u32_u24_e32 v2, 33, v74
	v_lshlrev_b32_e32 v2, 2, v2
	v_lshlrev_b32_e32 v3, 2, v73
	s_waitcnt vmcnt(0)
	v_cvt_pk_bf16_f32 v0, v60, v64
	v_add3_u32 v2, s11, v2, v3
	v_cvt_pk_bf16_f32 v52, v52, v56
	ds_write2_b32 v2, v0, v52 offset1:4
	v_cvt_pk_bf16_f32 v0, v53, v57
	v_cvt_pk_bf16_f32 v3, v61, v65
	ds_write2_b32 v2, v3, v0 offset0:33 offset1:37
	v_cvt_pk_bf16_f32 v0, v54, v58
	v_cvt_pk_bf16_f32 v60, v62, v66
	ds_write2_b32 v2, v60, v0 offset0:66 offset1:70
	v_cvt_pk_bf16_f32 v0, v55, v59
	v_cvt_pk_bf16_f32 v61, v63, v67
	ds_write2_b32 v2, v61, v0 offset0:99 offset1:103
	v_cvt_pk_bf16_f32 v0, v44, v48
	v_cvt_pk_bf16_f32 v36, v36, v40
	ds_write2_b32 v2, v0, v36 offset0:8 offset1:12
	v_cvt_pk_bf16_f32 v0, v37, v41
	v_cvt_pk_bf16_f32 v3, v45, v49
	ds_write2_b32 v2, v3, v0 offset0:41 offset1:45
	v_cvt_pk_bf16_f32 v0, v38, v42
	v_cvt_pk_bf16_f32 v44, v46, v50
	ds_write2_b32 v2, v44, v0 offset0:74 offset1:78
	v_cvt_pk_bf16_f32 v0, v39, v43
	v_cvt_pk_bf16_f32 v45, v47, v51
	ds_write2_b32 v2, v45, v0 offset0:107 offset1:111
	v_cvt_pk_bf16_f32 v0, v28, v32
	v_cvt_pk_bf16_f32 v20, v20, v24
	ds_write2_b32 v2, v0, v20 offset0:16 offset1:20
	v_cvt_pk_bf16_f32 v0, v21, v25
	v_cvt_pk_bf16_f32 v3, v29, v33
	ds_write2_b32 v2, v3, v0 offset0:49 offset1:53
	v_cvt_pk_bf16_f32 v0, v22, v26
	v_cvt_pk_bf16_f32 v28, v30, v34
	ds_write2_b32 v2, v28, v0 offset0:82 offset1:86
	v_cvt_pk_bf16_f32 v0, v23, v27
	v_cvt_pk_bf16_f32 v29, v31, v35
	ds_write2_b32 v2, v29, v0 offset0:115 offset1:119
	v_cvt_pk_bf16_f32 v0, v12, v16
	v_cvt_pk_bf16_f32 v4, v4, v8
	ds_write2_b32 v2, v0, v4 offset0:24 offset1:28
	v_cvt_pk_bf16_f32 v0, v5, v9
	v_cvt_pk_bf16_f32 v3, v13, v17
	ds_write2_b32 v2, v3, v0 offset0:57 offset1:61
	v_cvt_pk_bf16_f32 v0, v6, v10
	s_ashr_i32 s5, s4, 31
	v_cvt_pk_bf16_f32 v12, v14, v18
	ds_write2_b32 v2, v12, v0 offset0:90 offset1:94
	v_cvt_pk_bf16_f32 v0, v7, v11
	s_lshl_b64 s[4:5], s[4:5], 1
	v_cvt_pk_bf16_f32 v13, v15, v19
	ds_write2_b32 v2, v13, v0 offset0:123 offset1:127
	v_ashrrev_i32_e32 v6, 3, v72
	v_lshlrev_b32_e32 v0, 4, v72
	s_add_u32 s4, s9, s4
	s_mulk_i32 s31, 0x5600
	v_and_b32_e32 v0, 0x70, v0
	s_addc_u32 s5, s10, s5
	v_mul_lo_u32 v2, v6, s30
	v_subrev_u32_e32 v6, s31, v6
	v_lshl_add_u64 v[10:11], s[4:5], 0, v[0:1]
	v_add3_u32 v0, s11, v0, v2
	v_add_u32_e32 v12, s12, v6
	s_waitcnt lgkmcnt(0)
	ds_read2_b32 v[2:3], v0 offset1:1
	ds_read2_b32 v[4:5], v0 offset0:2 offset1:3
	v_subrev_u32_e32 v6, 56, v12
	v_ashrrev_i32_e32 v7, 31, v6
	v_lshlrev_b64 v[6:7], 13, v[6:7]
	v_lshl_add_u64 v[14:15], v[10:11], 0, v[6:7]
	v_add_u32_e32 v6, 0x420, v0
	v_add_u32_e32 v8, 0x428, v0
	ds_read2_b32 v[6:7], v6 offset1:1
	ds_read2_b32 v[8:9], v8 offset1:1
	s_waitcnt lgkmcnt(2)
	global_store_dwordx4 v[14:15], v[2:5], off nt
	v_ashrrev_i32_e32 v13, 31, v12
	s_add_i32 s3, s3, s8
	v_subrev_u32_e32 v2, 48, v12
	v_ashrrev_i32_e32 v3, 31, v2
	v_lshlrev_b64 v[2:3], 13, v[2:3]
	v_lshl_add_u64 v[2:3], v[10:11], 0, v[2:3]
	s_waitcnt lgkmcnt(0)
	global_store_dwordx4 v[2:3], v[6:9], off nt
	v_add_u32_e32 v2, 0x840, v0
	v_add_u32_e32 v4, 0x848, v0
	ds_read2_b32 v[2:3], v2 offset1:1
	ds_read2_b32 v[4:5], v4 offset1:1
	v_subrev_u32_e32 v6, 40, v12
	v_ashrrev_i32_e32 v7, 31, v6
	v_lshlrev_b64 v[6:7], 13, v[6:7]
	v_lshl_add_u64 v[14:15], v[10:11], 0, v[6:7]
	v_add_u32_e32 v6, 0xc60, v0
	v_add_u32_e32 v8, 0xc68, v0
	ds_read2_b32 v[6:7], v6 offset1:1
	ds_read2_b32 v[8:9], v8 offset1:1
	s_waitcnt lgkmcnt(2)
	global_store_dwordx4 v[14:15], v[2:5], off nt
	s_add_i32 s12, s12, s13
	s_add_i32 s14, s14, s15
	v_subrev_u32_e32 v2, 32, v12
	v_ashrrev_i32_e32 v3, 31, v2
	v_lshlrev_b64 v[2:3], 13, v[2:3]
	v_lshl_add_u64 v[2:3], v[10:11], 0, v[2:3]
	s_waitcnt lgkmcnt(0)
	global_store_dwordx4 v[2:3], v[6:9], off nt
	v_add_u32_e32 v2, 0x1080, v0
	v_add_u32_e32 v4, 0x1088, v0
	ds_read2_b32 v[2:3], v2 offset1:1
	ds_read2_b32 v[4:5], v4 offset1:1
	v_subrev_u32_e32 v6, 24, v12
	v_ashrrev_i32_e32 v7, 31, v6
	v_lshlrev_b64 v[6:7], 13, v[6:7]
	v_lshl_add_u64 v[14:15], v[10:11], 0, v[6:7]
	v_add_u32_e32 v6, 0x14a0, v0
	v_add_u32_e32 v8, 0x14a8, v0
	ds_read2_b32 v[6:7], v6 offset1:1
	ds_read2_b32 v[8:9], v8 offset1:1
	s_waitcnt lgkmcnt(2)
	global_store_dwordx4 v[14:15], v[2:5], off nt
	s_cmpk_lt_i32 s3, 0x5600
	s_nop 0
	v_add_u32_e32 v2, -16, v12
	v_ashrrev_i32_e32 v3, 31, v2
	v_lshlrev_b64 v[2:3], 13, v[2:3]
	v_lshl_add_u64 v[2:3], v[10:11], 0, v[2:3]
	s_waitcnt lgkmcnt(0)
	global_store_dwordx4 v[2:3], v[6:9], off nt
	v_add_u32_e32 v2, 0x18c0, v0
	v_add_u32_e32 v4, 0x18c8, v0
	v_add_u32_e32 v6, -8, v12
	v_ashrrev_i32_e32 v7, 31, v6
	ds_read2_b32 v[2:3], v2 offset1:1
	ds_read2_b32 v[4:5], v4 offset1:1
	v_lshlrev_b64 v[6:7], 13, v[6:7]
	v_lshl_add_u64 v[14:15], v[10:11], 0, v[6:7]
	v_add_u32_e32 v6, 0x1ce0, v0
	v_add_u32_e32 v0, 0x1ce8, v0
	ds_read2_b32 v[6:7], v6 offset1:1
	ds_read2_b32 v[8:9], v0 offset1:1
	s_waitcnt lgkmcnt(2)
	global_store_dwordx4 v[14:15], v[2:5], off nt
	s_nop 1
	v_lshlrev_b64 v[2:3], 13, v[12:13]
	v_lshl_add_u64 v[2:3], v[10:11], 0, v[2:3]
	s_waitcnt lgkmcnt(0)
	global_store_dwordx4 v[2:3], v[6:9], off nt
	s_waitcnt lgkmcnt(0)
	s_cbranch_scc0 .LBB0_1062

.LBB0_1355:
	s_waitcnt vmcnt(0)
	v_cvt_pk_bf16_f32 v56, v60, v56
	v_mul_u32_u24_e32 v60, 33, v68
	v_lshlrev_b32_e32 v60, 2, v60
	v_lshlrev_b32_e32 v64, 2, v67
	v_add3_u32 v60, s7, v60, v64
	v_cvt_pk_bf16_f32 v8, v16, v8
	v_cvt_pk_bf16_f32 v24, v28, v24
	ds_write2_b32 v60, v24, v8 offset0:16 offset1:20
	v_cvt_pk_bf16_f32 v8, v17, v9
	v_cvt_pk_bf16_f32 v25, v29, v25
	ds_write2_b32 v60, v25, v8 offset0:49 offset1:53
	v_cvt_pk_bf16_f32 v8, v18, v10
	v_cvt_pk_bf16_f32 v26, v30, v26
	ds_write2_b32 v60, v26, v8 offset0:82 offset1:86
	v_cvt_pk_bf16_f32 v8, v19, v11
	v_cvt_pk_bf16_f32 v0, v4, v0
	v_cvt_pk_bf16_f32 v27, v31, v27
	ds_write2_b32 v60, v27, v8 offset0:115 offset1:119
	v_cvt_pk_bf16_f32 v8, v20, v12
	ds_write2_b32 v60, v8, v0 offset0:24 offset1:28
	v_cvt_pk_bf16_f32 v0, v5, v1
	v_cvt_pk_bf16_f32 v9, v21, v13
	ds_write2_b32 v60, v9, v0 offset0:57 offset1:61
	v_cvt_pk_bf16_f32 v0, v6, v2
	v_cvt_pk_bf16_f32 v48, v52, v48
	v_cvt_pk_bf16_f32 v32, v36, v32
	v_cvt_pk_bf16_f32 v10, v22, v14
	ds_write2_b32 v60, v10, v0 offset0:90 offset1:94
	v_cvt_pk_bf16_f32 v0, v7, v3
	s_ashr_i32 s1, s0, 31
	ds_write2_b32 v60, v56, v48 offset1:4
	v_cvt_pk_bf16_f32 v48, v53, v49
	v_cvt_pk_bf16_f32 v40, v44, v40
	ds_write2_b32 v60, v40, v32 offset0:8 offset1:12
	v_cvt_pk_bf16_f32 v32, v37, v33
	v_cvt_pk_bf16_f32 v11, v23, v15
	ds_write2_b32 v60, v11, v0 offset0:123 offset1:127
	v_ashrrev_i32_e32 v4, 3, v66
	v_lshlrev_b32_e32 v0, 4, v66
	s_lshl_b64 s[0:1], s[0:1], 1
	v_cvt_pk_bf16_f32 v57, v61, v57
	ds_write2_b32 v60, v57, v48 offset0:33 offset1:37
	v_cvt_pk_bf16_f32 v48, v54, v50
	v_cvt_pk_bf16_f32 v41, v45, v41
	ds_write2_b32 v60, v41, v32 offset0:41 offset1:45
	v_cvt_pk_bf16_f32 v32, v38, v34
	v_and_b32_e32 v64, 0x70, v0
	s_add_u32 s0, s5, s0
	v_mul_lo_u32 v0, v4, s22
	v_subrev_u32_e32 v4, s24, v4
	v_cvt_pk_bf16_f32 v58, v62, v58
	v_cvt_pk_bf16_f32 v59, v63, v59
	ds_write2_b32 v60, v58, v48 offset0:66 offset1:70
	v_cvt_pk_bf16_f32 v48, v55, v51
	ds_write2_b32 v60, v59, v48 offset0:99 offset1:103
	v_cvt_pk_bf16_f32 v42, v46, v42
	v_cvt_pk_bf16_f32 v43, v47, v43
	ds_write2_b32 v60, v42, v32 offset0:74 offset1:78
	v_cvt_pk_bf16_f32 v32, v39, v35
	ds_write2_b32 v60, v43, v32 offset0:107 offset1:111
	s_addc_u32 s1, s6, s1
	v_add3_u32 v12, s7, v64, v0
	v_add_u32_e32 v13, s8, v4
	s_waitcnt lgkmcnt(0)
	v_lshl_add_u64 v[8:9], s[0:1], 0, v[64:65]
	ds_read2_b32 v[0:1], v12 offset1:1
	ds_read2_b32 v[2:3], v12 offset0:2 offset1:3
	v_subrev_u32_e32 v4, 56, v13
	v_mad_i64_i32 v[10:11], s[0:1], v4, s23, v[8:9]
	v_add_u32_e32 v4, 0x420, v12
	v_add_u32_e32 v6, 0x428, v12
	ds_read2_b32 v[4:5], v4 offset1:1
	ds_read2_b32 v[6:7], v6 offset1:1
	s_waitcnt lgkmcnt(2)
	global_store_dwordx4 v[10:11], v[0:3], off nt
	s_add_i32 s3, s3, s4
	s_add_i32 s8, s8, s9
	v_subrev_u32_e32 v0, 48, v13
	v_mad_i64_i32 v[0:1], s[0:1], v0, s23, v[8:9]
	s_waitcnt lgkmcnt(0)
	global_store_dwordx4 v[0:1], v[4:7], off nt
	v_add_u32_e32 v0, 0x840, v12
	v_add_u32_e32 v2, 0x848, v12
	ds_read2_b32 v[0:1], v0 offset1:1
	ds_read2_b32 v[2:3], v2 offset1:1
	v_subrev_u32_e32 v4, 40, v13
	v_mad_i64_i32 v[10:11], s[0:1], v4, s23, v[8:9]
	v_add_u32_e32 v4, 0xc60, v12
	v_add_u32_e32 v6, 0xc68, v12
	ds_read2_b32 v[4:5], v4 offset1:1
	ds_read2_b32 v[6:7], v6 offset1:1
	s_waitcnt lgkmcnt(2)
	global_store_dwordx4 v[10:11], v[0:3], off nt
	s_cmpk_lt_i32 s3, 0x2b00
	s_nop 0
	v_subrev_u32_e32 v0, 32, v13
	v_mad_i64_i32 v[0:1], s[0:1], v0, s23, v[8:9]
	s_waitcnt lgkmcnt(0)
	global_store_dwordx4 v[0:1], v[4:7], off nt
	v_add_u32_e32 v0, 0x1080, v12
	v_add_u32_e32 v2, 0x1088, v12
	ds_read2_b32 v[0:1], v0 offset1:1
	ds_read2_b32 v[2:3], v2 offset1:1
	v_subrev_u32_e32 v4, 24, v13
	v_mad_i64_i32 v[10:11], s[0:1], v4, s23, v[8:9]
	v_add_u32_e32 v4, 0x14a0, v12
	v_add_u32_e32 v6, 0x14a8, v12
	ds_read2_b32 v[4:5], v4 offset1:1
	ds_read2_b32 v[6:7], v6 offset1:1
	s_waitcnt lgkmcnt(2)
	global_store_dwordx4 v[10:11], v[0:3], off nt
	v_add_u32_e32 v10, -8, v13
	v_mad_i64_i32 v[10:11], s[0:1], v10, s23, v[8:9]
	v_add_u32_e32 v0, -16, v13
	v_mad_i64_i32 v[0:1], s[0:1], v0, s23, v[8:9]
	s_waitcnt lgkmcnt(0)
	global_store_dwordx4 v[0:1], v[4:7], off nt
	v_add_u32_e32 v0, 0x18c0, v12
	v_add_u32_e32 v2, 0x18c8, v12
	v_add_u32_e32 v4, 0x1ce0, v12
	v_add_u32_e32 v6, 0x1ce8, v12
	ds_read2_b32 v[0:1], v0 offset1:1
	ds_read2_b32 v[2:3], v2 offset1:1
	ds_read2_b32 v[4:5], v4 offset1:1
	ds_read2_b32 v[6:7], v6 offset1:1
	s_waitcnt lgkmcnt(2)
	global_store_dwordx4 v[10:11], v[0:3], off nt
	s_nop 1
	v_mad_i64_i32 v[0:1], s[0:1], v13, s23, v[8:9]
	s_waitcnt lgkmcnt(0)
	global_store_dwordx4 v[0:1], v[4:7], off nt
	s_waitcnt lgkmcnt(0)
	s_cbranch_scc0 .LBB0_1358

.LBB0_1757:
	s_waitcnt vmcnt(0)
	v_cvt_pk_bf16_f32 v56, v60, v56
	v_mul_u32_u24_e32 v60, 33, v68
	v_lshlrev_b32_e32 v60, 2, v60
	v_lshlrev_b32_e32 v64, 2, v67
	v_add3_u32 v60, s13, v60, v64
	v_cvt_pk_bf16_f32 v8, v16, v8
	v_cvt_pk_bf16_f32 v24, v28, v24
	ds_write2_b32 v60, v24, v8 offset0:16 offset1:20
	v_cvt_pk_bf16_f32 v8, v17, v9
	v_cvt_pk_bf16_f32 v25, v29, v25
	ds_write2_b32 v60, v25, v8 offset0:49 offset1:53
	v_cvt_pk_bf16_f32 v8, v18, v10
	v_cvt_pk_bf16_f32 v26, v30, v26
	ds_write2_b32 v60, v26, v8 offset0:82 offset1:86
	v_cvt_pk_bf16_f32 v8, v19, v11
	v_cvt_pk_bf16_f32 v0, v4, v0
	v_cvt_pk_bf16_f32 v27, v31, v27
	ds_write2_b32 v60, v27, v8 offset0:115 offset1:119
	v_cvt_pk_bf16_f32 v8, v20, v12
	ds_write2_b32 v60, v8, v0 offset0:24 offset1:28
	v_cvt_pk_bf16_f32 v0, v5, v1
	v_cvt_pk_bf16_f32 v9, v21, v13
	ds_write2_b32 v60, v9, v0 offset0:57 offset1:61
	v_cvt_pk_bf16_f32 v0, v6, v2
	v_cvt_pk_bf16_f32 v48, v52, v48
	v_cvt_pk_bf16_f32 v32, v36, v32
	v_cvt_pk_bf16_f32 v10, v22, v14
	ds_write2_b32 v60, v10, v0 offset0:90 offset1:94
	v_cvt_pk_bf16_f32 v0, v7, v3
	ds_write2_b32 v60, v56, v48 offset1:4
	v_cvt_pk_bf16_f32 v48, v53, v49
	v_cvt_pk_bf16_f32 v40, v44, v40
	ds_write2_b32 v60, v40, v32 offset0:8 offset1:12
	v_cvt_pk_bf16_f32 v32, v37, v33
	v_cvt_pk_bf16_f32 v11, v23, v15
	ds_write2_b32 v60, v11, v0 offset0:123 offset1:127
	v_ashrrev_i32_e32 v4, 3, v66
	v_lshlrev_b32_e32 v0, 4, v66
	v_cvt_pk_bf16_f32 v57, v61, v57
	ds_write2_b32 v60, v57, v48 offset0:33 offset1:37
	v_cvt_pk_bf16_f32 v48, v54, v50
	v_cvt_pk_bf16_f32 v41, v45, v41
	ds_write2_b32 v60, v41, v32 offset0:41 offset1:45
	v_cvt_pk_bf16_f32 v32, v38, v34
	v_and_b32_e32 v64, 0x70, v0
	s_ashr_i32 s7, s6, 31
	v_mul_lo_u32 v0, v4, s26
	v_subrev_u32_e32 v4, s30, v4
	v_cvt_pk_bf16_f32 v58, v62, v58
	v_cvt_pk_bf16_f32 v59, v63, v59
	ds_write2_b32 v60, v58, v48 offset0:66 offset1:70
	v_cvt_pk_bf16_f32 v48, v55, v51
	ds_write2_b32 v60, v59, v48 offset0:99 offset1:103
	v_cvt_pk_bf16_f32 v42, v46, v42
	v_cvt_pk_bf16_f32 v43, v47, v43
	ds_write2_b32 v60, v42, v32 offset0:74 offset1:78
	v_cvt_pk_bf16_f32 v32, v39, v35
	ds_write2_b32 v60, v43, v32 offset0:107 offset1:111
	s_lshl_b64 s[6:7], s[6:7], 1
	v_add3_u32 v11, s13, v64, v0
	v_add_u32_e32 v10, s27, v4
	s_waitcnt lgkmcnt(0)
	s_add_u32 s6, s8, s6
	ds_read2_b32 v[0:1], v11 offset1:1
	ds_read2_b32 v[2:3], v11 offset0:2 offset1:3
	v_subrev_u32_e32 v4, 56, v10
	s_addc_u32 s7, s9, s7
	v_ashrrev_i32_e32 v5, 31, v4
	v_lshl_add_u64 v[8:9], s[6:7], 0, v[64:65]
	v_lshlrev_b64 v[4:5], 13, v[4:5]
	v_lshl_add_u64 v[12:13], v[8:9], 0, v[4:5]
	v_add_u32_e32 v4, 0x420, v11
	v_add_u32_e32 v6, 0x428, v11
	ds_read2_b32 v[4:5], v4 offset1:1
	ds_read2_b32 v[6:7], v6 offset1:1
	s_waitcnt lgkmcnt(2)
	global_store_dwordx4 v[12:13], v[0:3], off nt
	s_add_i32 s29, s29, s12
	s_add_i32 s27, s27, s15
	v_subrev_u32_e32 v0, 48, v10
	v_ashrrev_i32_e32 v1, 31, v0
	v_lshlrev_b64 v[0:1], 13, v[0:1]
	v_lshl_add_u64 v[0:1], v[8:9], 0, v[0:1]
	s_waitcnt lgkmcnt(0)
	global_store_dwordx4 v[0:1], v[4:7], off nt
	v_add_u32_e32 v0, 0x840, v11
	v_add_u32_e32 v2, 0x848, v11
	ds_read2_b32 v[0:1], v0 offset1:1
	ds_read2_b32 v[2:3], v2 offset1:1
	v_subrev_u32_e32 v4, 40, v10
	v_ashrrev_i32_e32 v5, 31, v4
	v_lshlrev_b64 v[4:5], 13, v[4:5]
	v_lshl_add_u64 v[12:13], v[8:9], 0, v[4:5]
	v_add_u32_e32 v4, 0xc60, v11
	v_add_u32_e32 v6, 0xc68, v11
	ds_read2_b32 v[4:5], v4 offset1:1
	ds_read2_b32 v[6:7], v6 offset1:1
	s_waitcnt lgkmcnt(2)
	global_store_dwordx4 v[12:13], v[0:3], off nt
	s_cmpk_lt_i32 s29, 0x1000
	s_nop 0
	v_subrev_u32_e32 v0, 32, v10
	v_ashrrev_i32_e32 v1, 31, v0
	v_lshlrev_b64 v[0:1], 13, v[0:1]
	v_lshl_add_u64 v[0:1], v[8:9], 0, v[0:1]
	s_waitcnt lgkmcnt(0)
	global_store_dwordx4 v[0:1], v[4:7], off nt
	v_add_u32_e32 v0, 0x1080, v11
	v_add_u32_e32 v2, 0x1088, v11
	ds_read2_b32 v[0:1], v0 offset1:1
	ds_read2_b32 v[2:3], v2 offset1:1
	v_subrev_u32_e32 v4, 24, v10
	v_ashrrev_i32_e32 v5, 31, v4
	v_lshlrev_b64 v[4:5], 13, v[4:5]
	v_lshl_add_u64 v[12:13], v[8:9], 0, v[4:5]
	v_add_u32_e32 v4, 0x14a0, v11
	v_add_u32_e32 v6, 0x14a8, v11
	ds_read2_b32 v[4:5], v4 offset1:1
	ds_read2_b32 v[6:7], v6 offset1:1
	s_waitcnt lgkmcnt(2)
	global_store_dwordx4 v[12:13], v[0:3], off nt
	s_nop 1
	v_add_u32_e32 v0, -16, v10
	v_ashrrev_i32_e32 v1, 31, v0
	v_lshlrev_b64 v[0:1], 13, v[0:1]
	v_lshl_add_u64 v[0:1], v[8:9], 0, v[0:1]
	s_waitcnt lgkmcnt(0)
	global_store_dwordx4 v[0:1], v[4:7], off nt
	v_add_u32_e32 v0, 0x18c0, v11
	v_add_u32_e32 v2, 0x18c8, v11
	v_add_u32_e32 v4, -8, v10
	v_ashrrev_i32_e32 v5, 31, v4
	ds_read2_b32 v[0:1], v0 offset1:1
	ds_read2_b32 v[2:3], v2 offset1:1
	v_lshlrev_b64 v[4:5], 13, v[4:5]
	v_lshl_add_u64 v[12:13], v[8:9], 0, v[4:5]
	v_add_u32_e32 v4, 0x1ce0, v11
	v_add_u32_e32 v6, 0x1ce8, v11
	ds_read2_b32 v[4:5], v4 offset1:1
	ds_read2_b32 v[6:7], v6 offset1:1
	v_ashrrev_i32_e32 v11, 31, v10
	s_waitcnt lgkmcnt(2)
	global_store_dwordx4 v[12:13], v[0:3], off nt
	s_nop 1
	v_lshlrev_b64 v[0:1], 13, v[10:11]
	v_lshl_add_u64 v[0:1], v[8:9], 0, v[0:1]
	s_waitcnt lgkmcnt(0)
	global_store_dwordx4 v[0:1], v[4:7], off nt
	s_waitcnt lgkmcnt(0)
	s_cbranch_scc0 .LBB0_1760

.LBB0_1761:
	v_mul_u32_u24_e32 v2, 33, v72
	v_lshlrev_b32_e32 v2, 2, v2
	v_lshlrev_b32_e32 v3, 2, v71
	s_waitcnt vmcnt(14)
	v_cvt_pk_bf16_f32 v0, v60, v64
	v_add3_u32 v2, s13, v2, v3
	s_waitcnt vmcnt(12)
	v_cvt_pk_bf16_f32 v52, v52, v56
	ds_write2_b32 v2, v0, v52 offset1:4
	v_cvt_pk_bf16_f32 v0, v53, v57
	v_cvt_pk_bf16_f32 v3, v61, v65
	ds_write2_b32 v2, v3, v0 offset0:33 offset1:37
	v_cvt_pk_bf16_f32 v0, v54, v58
	v_cvt_pk_bf16_f32 v60, v62, v66
	ds_write2_b32 v2, v60, v0 offset0:66 offset1:70
	v_cvt_pk_bf16_f32 v0, v55, v59
	v_cvt_pk_bf16_f32 v61, v63, v67
	ds_write2_b32 v2, v61, v0 offset0:99 offset1:103
	s_waitcnt vmcnt(10)
	v_cvt_pk_bf16_f32 v0, v44, v48
	s_waitcnt vmcnt(8)
	v_cvt_pk_bf16_f32 v36, v36, v40
	ds_write2_b32 v2, v0, v36 offset0:8 offset1:12
	v_cvt_pk_bf16_f32 v0, v37, v41
	v_cvt_pk_bf16_f32 v3, v45, v49
	ds_write2_b32 v2, v3, v0 offset0:41 offset1:45
	v_cvt_pk_bf16_f32 v0, v38, v42
	v_cvt_pk_bf16_f32 v44, v46, v50
	ds_write2_b32 v2, v44, v0 offset0:74 offset1:78
	v_cvt_pk_bf16_f32 v0, v39, v43
	v_cvt_pk_bf16_f32 v45, v47, v51
	ds_write2_b32 v2, v45, v0 offset0:107 offset1:111
	s_waitcnt vmcnt(6)
	v_cvt_pk_bf16_f32 v0, v28, v32
	s_waitcnt vmcnt(4)
	v_cvt_pk_bf16_f32 v20, v20, v24
	ds_write2_b32 v2, v0, v20 offset0:16 offset1:20
	v_cvt_pk_bf16_f32 v0, v21, v25
	v_cvt_pk_bf16_f32 v3, v29, v33
	ds_write2_b32 v2, v3, v0 offset0:49 offset1:53
	v_cvt_pk_bf16_f32 v0, v22, v26
	v_cvt_pk_bf16_f32 v28, v30, v34
	ds_write2_b32 v2, v28, v0 offset0:82 offset1:86
	v_cvt_pk_bf16_f32 v0, v23, v27
	v_cvt_pk_bf16_f32 v29, v31, v35
	ds_write2_b32 v2, v29, v0 offset0:115 offset1:119
	s_waitcnt vmcnt(2)
	v_cvt_pk_bf16_f32 v0, v12, v16
	s_waitcnt vmcnt(0)
	v_cvt_pk_bf16_f32 v4, v4, v8
	ds_write2_b32 v2, v0, v4 offset0:24 offset1:28
	v_cvt_pk_bf16_f32 v0, v5, v9
	v_cvt_pk_bf16_f32 v3, v13, v17
	ds_write2_b32 v2, v3, v0 offset0:57 offset1:61
	v_cvt_pk_bf16_f32 v0, v6, v10
	s_ashr_i32 s11, s10, 31
	v_cvt_pk_bf16_f32 v12, v14, v18
	ds_write2_b32 v2, v12, v0 offset0:90 offset1:94
	v_cvt_pk_bf16_f32 v0, v7, v11
	s_lshl_b64 s[10:11], s[10:11], 1
	v_cvt_pk_bf16_f32 v13, v15, v19
	ds_write2_b32 v2, v13, v0 offset0:123 offset1:127
	v_ashrrev_i32_e32 v6, 3, v70
	v_lshlrev_b32_e32 v0, 4, v70
	s_add_u32 s10, s16, s10
	v_and_b32_e32 v0, 0x70, v0
	s_addc_u32 s11, s17, s11
	v_mul_lo_u32 v2, v6, s31
	v_subrev_u32_e32 v6, s33, v6
	v_lshl_add_u64 v[10:11], s[10:11], 0, v[0:1]
	v_add3_u32 v0, s13, v0, v2
	v_add_u32_e32 v12, s14, v6
	s_waitcnt lgkmcnt(0)
	ds_read2_b32 v[2:3], v0 offset1:1
	ds_read2_b32 v[4:5], v0 offset0:2 offset1:3
	v_subrev_u32_e32 v6, 56, v12
	v_ashrrev_i32_e32 v7, 31, v6
	v_lshlrev_b64 v[6:7], 13, v[6:7]
	v_lshl_add_u64 v[14:15], v[10:11], 0, v[6:7]
	v_add_u32_e32 v6, 0x420, v0
	v_add_u32_e32 v8, 0x428, v0
	ds_read2_b32 v[6:7], v6 offset1:1
	ds_read2_b32 v[8:9], v8 offset1:1
	s_waitcnt lgkmcnt(2)
	global_store_dwordx4 v[14:15], v[2:5], off nt
	v_ashrrev_i32_e32 v13, 31, v12
	s_add_i32 s3, s3, s12
	v_subrev_u32_e32 v2, 48, v12
	v_ashrrev_i32_e32 v3, 31, v2
	v_lshlrev_b64 v[2:3], 13, v[2:3]
	v_lshl_add_u64 v[2:3], v[10:11], 0, v[2:3]
	s_waitcnt lgkmcnt(0)
	global_store_dwordx4 v[2:3], v[6:9], off nt
	v_add_u32_e32 v2, 0x840, v0
	v_add_u32_e32 v4, 0x848, v0
	ds_read2_b32 v[2:3], v2 offset1:1
	ds_read2_b32 v[4:5], v4 offset1:1
	v_subrev_u32_e32 v6, 40, v12
	v_ashrrev_i32_e32 v7, 31, v6
	v_lshlrev_b64 v[6:7], 13, v[6:7]
	v_lshl_add_u64 v[14:15], v[10:11], 0, v[6:7]
	v_add_u32_e32 v6, 0xc60, v0
	v_add_u32_e32 v8, 0xc68, v0
	ds_read2_b32 v[6:7], v6 offset1:1
	ds_read2_b32 v[8:9], v8 offset1:1
	s_waitcnt lgkmcnt(2)
	global_store_dwordx4 v[14:15], v[2:5], off nt
	s_add_i32 s14, s14, s15
	s_cmpk_lt_i32 s3, 0x1000
	v_subrev_u32_e32 v2, 32, v12
	v_ashrrev_i32_e32 v3, 31, v2
	v_lshlrev_b64 v[2:3], 13, v[2:3]
	v_lshl_add_u64 v[2:3], v[10:11], 0, v[2:3]
	s_waitcnt lgkmcnt(0)
	global_store_dwordx4 v[2:3], v[6:9], off nt
	v_add_u32_e32 v2, 0x1080, v0
	v_add_u32_e32 v4, 0x1088, v0
	ds_read2_b32 v[2:3], v2 offset1:1
	ds_read2_b32 v[4:5], v4 offset1:1
	v_subrev_u32_e32 v6, 24, v12
	v_ashrrev_i32_e32 v7, 31, v6
	v_lshlrev_b64 v[6:7], 13, v[6:7]
	v_lshl_add_u64 v[14:15], v[10:11], 0, v[6:7]
	v_add_u32_e32 v6, 0x14a0, v0
	v_add_u32_e32 v8, 0x14a8, v0
	ds_read2_b32 v[6:7], v6 offset1:1
	ds_read2_b32 v[8:9], v8 offset1:1
	s_waitcnt lgkmcnt(2)
	global_store_dwordx4 v[14:15], v[2:5], off nt
	s_nop 1
	v_add_u32_e32 v2, -16, v12
	v_ashrrev_i32_e32 v3, 31, v2
	v_lshlrev_b64 v[2:3], 13, v[2:3]
	v_lshl_add_u64 v[2:3], v[10:11], 0, v[2:3]
	s_waitcnt lgkmcnt(0)
	global_store_dwordx4 v[2:3], v[6:9], off nt
	v_add_u32_e32 v2, 0x18c0, v0
	v_add_u32_e32 v4, 0x18c8, v0
	v_add_u32_e32 v6, -8, v12
	v_ashrrev_i32_e32 v7, 31, v6
	ds_read2_b32 v[2:3], v2 offset1:1
	ds_read2_b32 v[4:5], v4 offset1:1
	v_lshlrev_b64 v[6:7], 13, v[6:7]
	v_lshl_add_u64 v[14:15], v[10:11], 0, v[6:7]
	v_add_u32_e32 v6, 0x1ce0, v0
	v_add_u32_e32 v0, 0x1ce8, v0
	ds_read2_b32 v[6:7], v6 offset1:1
	ds_read2_b32 v[8:9], v0 offset1:1
	s_waitcnt lgkmcnt(2)
	global_store_dwordx4 v[14:15], v[2:5], off nt
	s_nop 1
	v_lshlrev_b64 v[2:3], 13, v[12:13]
	v_lshl_add_u64 v[2:3], v[10:11], 0, v[2:3]
	s_waitcnt lgkmcnt(0)
	global_store_dwordx4 v[2:3], v[6:9], off nt
	s_waitcnt lgkmcnt(0)
	s_cbranch_scc0 .LBB0_1766

.LBB0_2629:
	v_mul_u32_u24_e32 v2, 33, v74
	v_lshlrev_b32_e32 v2, 2, v2
	v_lshlrev_b32_e32 v3, 2, v73
	s_waitcnt vmcnt(0)
	v_cvt_pk_bf16_f32 v0, v60, v64
	v_add3_u32 v2, s13, v2, v3
	v_cvt_pk_bf16_f32 v52, v52, v56
	ds_write2_b32 v2, v0, v52 offset1:4
	v_cvt_pk_bf16_f32 v0, v53, v57
	v_cvt_pk_bf16_f32 v3, v61, v65
	ds_write2_b32 v2, v3, v0 offset0:33 offset1:37
	v_cvt_pk_bf16_f32 v0, v54, v58
	v_cvt_pk_bf16_f32 v60, v62, v66
	ds_write2_b32 v2, v60, v0 offset0:66 offset1:70
	v_cvt_pk_bf16_f32 v0, v55, v59
	v_cvt_pk_bf16_f32 v61, v63, v67
	ds_write2_b32 v2, v61, v0 offset0:99 offset1:103
	v_cvt_pk_bf16_f32 v0, v44, v48
	v_cvt_pk_bf16_f32 v36, v36, v40
	ds_write2_b32 v2, v0, v36 offset0:8 offset1:12
	v_cvt_pk_bf16_f32 v0, v37, v41
	v_cvt_pk_bf16_f32 v3, v45, v49
	ds_write2_b32 v2, v3, v0 offset0:41 offset1:45
	v_cvt_pk_bf16_f32 v0, v38, v42
	v_cvt_pk_bf16_f32 v44, v46, v50
	ds_write2_b32 v2, v44, v0 offset0:74 offset1:78
	v_cvt_pk_bf16_f32 v0, v39, v43
	v_cvt_pk_bf16_f32 v45, v47, v51
	ds_write2_b32 v2, v45, v0 offset0:107 offset1:111
	v_cvt_pk_bf16_f32 v0, v28, v32
	v_cvt_pk_bf16_f32 v20, v20, v24
	ds_write2_b32 v2, v0, v20 offset0:16 offset1:20
	v_cvt_pk_bf16_f32 v0, v21, v25
	v_cvt_pk_bf16_f32 v3, v29, v33
	ds_write2_b32 v2, v3, v0 offset0:49 offset1:53
	v_cvt_pk_bf16_f32 v0, v22, v26
	v_cvt_pk_bf16_f32 v28, v30, v34
	ds_write2_b32 v2, v28, v0 offset0:82 offset1:86
	v_cvt_pk_bf16_f32 v0, v23, v27
	v_cvt_pk_bf16_f32 v29, v31, v35
	ds_write2_b32 v2, v29, v0 offset0:115 offset1:119
	v_cvt_pk_bf16_f32 v0, v12, v16
	v_cvt_pk_bf16_f32 v4, v4, v8
	ds_write2_b32 v2, v0, v4 offset0:24 offset1:28
	v_cvt_pk_bf16_f32 v0, v5, v9
	v_cvt_pk_bf16_f32 v3, v13, v17
	ds_write2_b32 v2, v3, v0 offset0:57 offset1:61
	v_cvt_pk_bf16_f32 v0, v6, v10
	s_ashr_i32 s9, s8, 31
	v_cvt_pk_bf16_f32 v12, v14, v18
	ds_write2_b32 v2, v12, v0 offset0:90 offset1:94
	v_cvt_pk_bf16_f32 v0, v7, v11
	s_lshl_b64 s[8:9], s[8:9], 1
	v_cvt_pk_bf16_f32 v13, v15, v19
	ds_write2_b32 v2, v13, v0 offset0:123 offset1:127
	v_ashrrev_i32_e32 v6, 3, v72
	v_lshlrev_b32_e32 v0, 4, v72
	s_add_u32 s8, s11, s8
	s_mulk_i32 s34, 0x5600
	v_and_b32_e32 v0, 0x70, v0
	s_addc_u32 s9, s12, s9
	v_mul_lo_u32 v2, v6, s33
	v_subrev_u32_e32 v6, s34, v6
	v_lshl_add_u64 v[10:11], s[8:9], 0, v[0:1]
	v_add3_u32 v0, s13, v0, v2
	v_add_u32_e32 v12, s14, v6
	s_waitcnt lgkmcnt(0)
	ds_read2_b32 v[2:3], v0 offset1:1
	ds_read2_b32 v[4:5], v0 offset0:2 offset1:3
	v_subrev_u32_e32 v6, 56, v12
	v_ashrrev_i32_e32 v7, 31, v6
	v_lshlrev_b64 v[6:7], 13, v[6:7]
	v_lshl_add_u64 v[14:15], v[10:11], 0, v[6:7]
	v_add_u32_e32 v6, 0x420, v0
	v_add_u32_e32 v8, 0x428, v0
	ds_read2_b32 v[6:7], v6 offset1:1
	ds_read2_b32 v[8:9], v8 offset1:1
	s_waitcnt lgkmcnt(2)
	global_store_dwordx4 v[14:15], v[2:5], off nt
	v_ashrrev_i32_e32 v13, 31, v12
	s_add_i32 s3, s3, s10
	v_subrev_u32_e32 v2, 48, v12
	v_ashrrev_i32_e32 v3, 31, v2
	v_lshlrev_b64 v[2:3], 13, v[2:3]
	v_lshl_add_u64 v[2:3], v[10:11], 0, v[2:3]
	s_waitcnt lgkmcnt(0)
	global_store_dwordx4 v[2:3], v[6:9], off nt
	v_add_u32_e32 v2, 0x840, v0
	v_add_u32_e32 v4, 0x848, v0
	ds_read2_b32 v[2:3], v2 offset1:1
	ds_read2_b32 v[4:5], v4 offset1:1
	v_subrev_u32_e32 v6, 40, v12
	v_ashrrev_i32_e32 v7, 31, v6
	v_lshlrev_b64 v[6:7], 13, v[6:7]
	v_lshl_add_u64 v[14:15], v[10:11], 0, v[6:7]
	v_add_u32_e32 v6, 0xc60, v0
	v_add_u32_e32 v8, 0xc68, v0
	ds_read2_b32 v[6:7], v6 offset1:1
	ds_read2_b32 v[8:9], v8 offset1:1
	s_waitcnt lgkmcnt(2)
	global_store_dwordx4 v[14:15], v[2:5], off nt
	s_add_i32 s14, s14, s15
	s_add_i32 s16, s16, s17
	v_subrev_u32_e32 v2, 32, v12
	v_ashrrev_i32_e32 v3, 31, v2
	v_lshlrev_b64 v[2:3], 13, v[2:3]
	v_lshl_add_u64 v[2:3], v[10:11], 0, v[2:3]
	s_waitcnt lgkmcnt(0)
	global_store_dwordx4 v[2:3], v[6:9], off nt
	v_add_u32_e32 v2, 0x1080, v0
	v_add_u32_e32 v4, 0x1088, v0
	ds_read2_b32 v[2:3], v2 offset1:1
	ds_read2_b32 v[4:5], v4 offset1:1
	v_subrev_u32_e32 v6, 24, v12
	v_ashrrev_i32_e32 v7, 31, v6
	v_lshlrev_b64 v[6:7], 13, v[6:7]
	v_lshl_add_u64 v[14:15], v[10:11], 0, v[6:7]
	v_add_u32_e32 v6, 0x14a0, v0
	v_add_u32_e32 v8, 0x14a8, v0
	ds_read2_b32 v[6:7], v6 offset1:1
	ds_read2_b32 v[8:9], v8 offset1:1
	s_waitcnt lgkmcnt(2)
	global_store_dwordx4 v[14:15], v[2:5], off nt
	s_cmpk_lt_i32 s3, 0x5600
	s_nop 0
	v_add_u32_e32 v2, -16, v12
	v_ashrrev_i32_e32 v3, 31, v2
	v_lshlrev_b64 v[2:3], 13, v[2:3]
	v_lshl_add_u64 v[2:3], v[10:11], 0, v[2:3]
	s_waitcnt lgkmcnt(0)
	global_store_dwordx4 v[2:3], v[6:9], off nt
	v_add_u32_e32 v2, 0x18c0, v0
	v_add_u32_e32 v4, 0x18c8, v0
	v_add_u32_e32 v6, -8, v12
	v_ashrrev_i32_e32 v7, 31, v6
	ds_read2_b32 v[2:3], v2 offset1:1
	ds_read2_b32 v[4:5], v4 offset1:1
	v_lshlrev_b64 v[6:7], 13, v[6:7]
	v_lshl_add_u64 v[14:15], v[10:11], 0, v[6:7]
	v_add_u32_e32 v6, 0x1ce0, v0
	v_add_u32_e32 v0, 0x1ce8, v0
	ds_read2_b32 v[6:7], v6 offset1:1
	ds_read2_b32 v[8:9], v0 offset1:1
	s_waitcnt lgkmcnt(2)
	global_store_dwordx4 v[14:15], v[2:5], off nt
	s_nop 1
	v_lshlrev_b64 v[2:3], 13, v[12:13]
	v_lshl_add_u64 v[2:3], v[10:11], 0, v[2:3]
	s_waitcnt lgkmcnt(0)
	global_store_dwordx4 v[2:3], v[6:9], off nt
	s_waitcnt lgkmcnt(0)
	s_cbranch_scc0 .LBB0_2634

.LBB0_2927:
	s_waitcnt vmcnt(0)
	v_cvt_pk_bf16_f32 v56, v60, v56
	v_mul_u32_u24_e32 v60, 33, v68
	v_lshlrev_b32_e32 v60, 2, v60
	v_lshlrev_b32_e32 v64, 2, v67
	v_add3_u32 v60, s9, v60, v64
	v_cvt_pk_bf16_f32 v8, v16, v8
	v_cvt_pk_bf16_f32 v24, v28, v24
	ds_write2_b32 v60, v24, v8 offset0:16 offset1:20
	v_cvt_pk_bf16_f32 v8, v17, v9
	v_cvt_pk_bf16_f32 v25, v29, v25
	ds_write2_b32 v60, v25, v8 offset0:49 offset1:53
	v_cvt_pk_bf16_f32 v8, v18, v10
	v_cvt_pk_bf16_f32 v26, v30, v26
	ds_write2_b32 v60, v26, v8 offset0:82 offset1:86
	v_cvt_pk_bf16_f32 v8, v19, v11
	v_cvt_pk_bf16_f32 v0, v4, v0
	v_cvt_pk_bf16_f32 v27, v31, v27
	ds_write2_b32 v60, v27, v8 offset0:115 offset1:119
	v_cvt_pk_bf16_f32 v8, v20, v12
	ds_write2_b32 v60, v8, v0 offset0:24 offset1:28
	v_cvt_pk_bf16_f32 v0, v5, v1
	v_cvt_pk_bf16_f32 v9, v21, v13
	ds_write2_b32 v60, v9, v0 offset0:57 offset1:61
	v_cvt_pk_bf16_f32 v0, v6, v2
	v_cvt_pk_bf16_f32 v48, v52, v48
	v_cvt_pk_bf16_f32 v32, v36, v32
	v_cvt_pk_bf16_f32 v10, v22, v14
	ds_write2_b32 v60, v10, v0 offset0:90 offset1:94
	v_cvt_pk_bf16_f32 v0, v7, v3
	s_ashr_i32 s5, s4, 31
	ds_write2_b32 v60, v56, v48 offset1:4
	v_cvt_pk_bf16_f32 v48, v53, v49
	v_cvt_pk_bf16_f32 v40, v44, v40
	ds_write2_b32 v60, v40, v32 offset0:8 offset1:12
	v_cvt_pk_bf16_f32 v32, v37, v33
	v_cvt_pk_bf16_f32 v11, v23, v15
	ds_write2_b32 v60, v11, v0 offset0:123 offset1:127
	v_ashrrev_i32_e32 v4, 3, v66
	v_lshlrev_b32_e32 v0, 4, v66
	s_lshl_b64 s[4:5], s[4:5], 1
	v_cvt_pk_bf16_f32 v57, v61, v57
	ds_write2_b32 v60, v57, v48 offset0:33 offset1:37
	v_cvt_pk_bf16_f32 v48, v54, v50
	v_cvt_pk_bf16_f32 v41, v45, v41
	ds_write2_b32 v60, v41, v32 offset0:41 offset1:45
	v_cvt_pk_bf16_f32 v32, v38, v34
	v_and_b32_e32 v64, 0x70, v0
	s_add_u32 s4, s7, s4
	v_mul_lo_u32 v0, v4, s26
	v_subrev_u32_e32 v4, s29, v4
	v_cvt_pk_bf16_f32 v58, v62, v58
	v_cvt_pk_bf16_f32 v59, v63, v59
	ds_write2_b32 v60, v58, v48 offset0:66 offset1:70
	v_cvt_pk_bf16_f32 v48, v55, v51
	ds_write2_b32 v60, v59, v48 offset0:99 offset1:103
	v_cvt_pk_bf16_f32 v42, v46, v42
	v_cvt_pk_bf16_f32 v43, v47, v43
	ds_write2_b32 v60, v42, v32 offset0:74 offset1:78
	v_cvt_pk_bf16_f32 v32, v39, v35
	ds_write2_b32 v60, v43, v32 offset0:107 offset1:111
	s_addc_u32 s5, s8, s5
	v_add3_u32 v12, s9, v64, v0
	v_add_u32_e32 v13, s10, v4
	s_waitcnt lgkmcnt(0)
	v_lshl_add_u64 v[8:9], s[4:5], 0, v[64:65]
	ds_read2_b32 v[0:1], v12 offset1:1
	ds_read2_b32 v[2:3], v12 offset0:2 offset1:3
	v_subrev_u32_e32 v4, 56, v13
	v_mad_i64_i32 v[10:11], s[4:5], v4, s27, v[8:9]
	v_add_u32_e32 v4, 0x420, v12
	v_add_u32_e32 v6, 0x428, v12
	ds_read2_b32 v[4:5], v4 offset1:1
	ds_read2_b32 v[6:7], v6 offset1:1
	s_waitcnt lgkmcnt(2)
	global_store_dwordx4 v[10:11], v[0:3], off nt
	s_add_i32 s3, s3, s6
	s_add_i32 s10, s10, s11
	v_subrev_u32_e32 v0, 48, v13
	v_mad_i64_i32 v[0:1], s[4:5], v0, s27, v[8:9]
	s_waitcnt lgkmcnt(0)
	global_store_dwordx4 v[0:1], v[4:7], off nt
	v_add_u32_e32 v0, 0x840, v12
	v_add_u32_e32 v2, 0x848, v12
	ds_read2_b32 v[0:1], v0 offset1:1
	ds_read2_b32 v[2:3], v2 offset1:1
	v_subrev_u32_e32 v4, 40, v13
	v_mad_i64_i32 v[10:11], s[4:5], v4, s27, v[8:9]
	v_add_u32_e32 v4, 0xc60, v12
	v_add_u32_e32 v6, 0xc68, v12
	ds_read2_b32 v[4:5], v4 offset1:1
	ds_read2_b32 v[6:7], v6 offset1:1
	s_waitcnt lgkmcnt(2)
	global_store_dwordx4 v[10:11], v[0:3], off nt
	s_cmpk_lt_i32 s3, 0x2b00
	s_nop 0
	v_subrev_u32_e32 v0, 32, v13
	v_mad_i64_i32 v[0:1], s[4:5], v0, s27, v[8:9]
	s_waitcnt lgkmcnt(0)
	global_store_dwordx4 v[0:1], v[4:7], off nt
	v_add_u32_e32 v0, 0x1080, v12
	v_add_u32_e32 v2, 0x1088, v12
	ds_read2_b32 v[0:1], v0 offset1:1
	ds_read2_b32 v[2:3], v2 offset1:1
	v_subrev_u32_e32 v4, 24, v13
	v_mad_i64_i32 v[10:11], s[4:5], v4, s27, v[8:9]
	v_add_u32_e32 v4, 0x14a0, v12
	v_add_u32_e32 v6, 0x14a8, v12
	ds_read2_b32 v[4:5], v4 offset1:1
	ds_read2_b32 v[6:7], v6 offset1:1
	s_waitcnt lgkmcnt(2)
	global_store_dwordx4 v[10:11], v[0:3], off nt
	v_add_u32_e32 v10, -8, v13
	v_mad_i64_i32 v[10:11], s[4:5], v10, s27, v[8:9]
	v_add_u32_e32 v0, -16, v13
	v_mad_i64_i32 v[0:1], s[4:5], v0, s27, v[8:9]
	s_waitcnt lgkmcnt(0)
	global_store_dwordx4 v[0:1], v[4:7], off nt
	v_add_u32_e32 v0, 0x18c0, v12
	v_add_u32_e32 v2, 0x18c8, v12
	v_add_u32_e32 v4, 0x1ce0, v12
	v_add_u32_e32 v6, 0x1ce8, v12
	ds_read2_b32 v[0:1], v0 offset1:1
	ds_read2_b32 v[2:3], v2 offset1:1
	ds_read2_b32 v[4:5], v4 offset1:1
	ds_read2_b32 v[6:7], v6 offset1:1
	s_waitcnt lgkmcnt(2)
	global_store_dwordx4 v[10:11], v[0:3], off nt
	s_nop 1
	v_mad_i64_i32 v[0:1], s[4:5], v13, s27, v[8:9]
	s_waitcnt lgkmcnt(0)
	global_store_dwordx4 v[0:1], v[4:7], off nt
	s_waitcnt lgkmcnt(0)
	s_cbranch_scc0 .LBB0_2930
